# adds: nt (streaming) hint on the final f32 output stores of P6
# speedup vs baseline: 1.0041x; 1.0037x over previous
.LBB0_922:
	s_mulk_i32 s28, 0x900
	s_add_i32 s0, s28, 0
	s_movk_i32 s1, 0x90
	v_mov_b32_e32 v215, s0
	v_lshrrev_b32_e32 v220, 3, v1
	v_and_b32_e32 v1, 7, v0
	v_mad_u32_u24 v218, v213, s1, v215
	v_lshlrev_b32_e32 v213, 2, v1
	s_ashr_i32 s5, s4, 31
	v_lshlrev_b32_e32 v219, 5, v214
	v_mad_u32_u24 v221, v220, s1, v215
	s_ashr_i32 s7, s6, 31
	v_lshlrev_b32_e32 v214, 16, v206
	v_and_b32_e32 v215, 0xffff0000, v206
	v_lshlrev_b32_e32 v206, 16, v207
	v_and_b32_e32 v207, 0xffff0000, v207
	v_lshlrev_b32_e32 v216, 16, v208
	v_and_b32_e32 v217, 0xffff0000, v208
	s_waitcnt lgkmcnt(0)
	v_pk_mul_f32 v[128:129], v[128:129], v[212:213] op_sel_hi:[1,0]
	v_pk_mul_f32 v[126:127], v[126:127], v[212:213] op_sel_hi:[1,0]
	v_pk_mul_f32 v[122:123], v[122:123], v[212:213] op_sel_hi:[1,0]
	s_lshl_b64 s[0:1], s[4:5], 12
	v_lshlrev_b32_e32 v208, 16, v209
	v_and_b32_e32 v209, 0xffff0000, v209
	v_pk_fma_f32 v[128:129], v[196:197], v[128:129], v[206:207]
	v_pk_fma_f32 v[126:127], v[194:195], v[126:127], v[214:215]
	v_pk_mul_f32 v[124:125], v[124:125], v[212:213] op_sel_hi:[1,0]
	v_pk_fma_f32 v[206:207], v[190:191], v[122:123], v[216:217]
	v_add_u32_e32 v122, v218, v219
	s_add_u32 s0, s58, s0
	v_lshlrev_b32_e32 v0, 4, v1
	v_pk_fma_f32 v[208:209], v[192:193], v[124:125], v[208:209]
	ds_write_b128 v122, v[126:129] offset:16384
	ds_write_b128 v122, v[206:209] offset:16400
	s_addc_u32 s1, s59, s1
	s_lshl_b64 s[6:7], s[6:7], 2
	v_add_u32_e32 v223, 0x480, v221
	s_waitcnt lgkmcnt(0)
	v_add_u32_e32 v123, v221, v0
	s_add_u32 s0, s0, s6
	v_add_u32_e32 v124, v223, v0
	ds_read_b128 v[126:129], v123 offset:16384
	ds_read_b128 v[206:209], v124 offset:16384
	s_addc_u32 s1, s1, s7
	s_lshl_b32 s5, s18, 2
	s_add_u32 s0, s0, s5
	v_mov_b32_e32 v1, 0
	s_addc_u32 s1, s1, 0
	v_or_b32_e32 v222, 8, v220
	s_waitcnt lgkmcnt(0)
	v_lshl_add_u64 v[214:215], s[0:1], 0, v[0:1]
	v_lshlrev_b32_e32 v0, 12, v220
	v_lshl_add_u64 v[216:217], v[214:215], 0, v[0:1]
	s_waitcnt lgkmcnt(1)
	global_store_dwordx4 v[216:217], v[126:129], off sc1 nt
	s_nop 1
	v_lshlrev_b32_e32 v128, 12, v222
	v_mov_b32_e32 v129, v1
	v_lshl_add_u64 v[216:217], v[214:215], 0, v[128:129]
	s_waitcnt lgkmcnt(0)
	global_store_dwordx4 v[216:217], v[206:209], off sc1 nt
	s_nop 1
	v_lshlrev_b32_e32 v206, 16, v202
	v_and_b32_e32 v207, 0xffff0000, v202
	v_lshlrev_b32_e32 v202, 16, v203
	v_and_b32_e32 v203, 0xffff0000, v203
	v_pk_mul_f32 v[120:121], v[120:121], v[212:213] op_sel_hi:[1,0]
	v_pk_mul_f32 v[118:119], v[118:119], v[212:213] op_sel_hi:[1,0]
	v_lshlrev_b32_e32 v208, 16, v204
	v_and_b32_e32 v209, 0xffff0000, v204
	v_lshlrev_b32_e32 v204, 16, v205
	v_and_b32_e32 v205, 0xffff0000, v205
	v_pk_fma_f32 v[120:121], v[184:185], v[120:121], v[202:203]
	v_pk_fma_f32 v[118:119], v[182:183], v[118:119], v[206:207]
	v_pk_mul_f32 v[116:117], v[116:117], v[212:213] op_sel_hi:[1,0]
	v_pk_mul_f32 v[114:115], v[114:115], v[212:213] op_sel_hi:[1,0]
	v_pk_fma_f32 v[116:117], v[180:181], v[116:117], v[204:205]
	v_pk_fma_f32 v[114:115], v[178:179], v[114:115], v[208:209]
	ds_write_b128 v122, v[118:121] offset:16384
	ds_write_b128 v122, v[114:117] offset:16400
	s_waitcnt lgkmcnt(0)
	ds_read_b128 v[114:117], v123 offset:16384
	ds_read_b128 v[118:121], v124 offset:16384
	s_mov_b64 s[8:9], 0x200
	s_waitcnt lgkmcnt(0)
	v_lshl_add_u64 v[202:203], v[214:215], 0, s[8:9]
	v_lshl_add_u64 v[204:205], v[202:203], 0, v[0:1]
	s_waitcnt lgkmcnt(1)
	global_store_dwordx4 v[204:205], v[114:117], off sc1 nt
	s_nop 1
	v_lshl_add_u64 v[114:115], v[202:203], 0, v[128:129]
	s_waitcnt lgkmcnt(0)
	global_store_dwordx4 v[114:115], v[118:121], off sc1 nt
	s_nop 1
	v_cndmask_b32_e64 v0, 0, 1, s[2:3]
	v_lshlrev_b32_e32 v125, 10, v220
	v_lshlrev_b32_e32 v126, 10, v222
	v_cmp_ne_u32_e64 s[0:1], 1, v0
	s_andn2_b64 vcc, exec, s[2:3]
	s_cbranch_vccnz .LBB0_924
	ds_read_b32 v210, v211 offset:8256
.LBB0_924:
	s_or_b32 s2, s4, 16
	s_ashr_i32 s3, s2, 31
	v_lshlrev_b32_e32 v114, 16, v198
	v_and_b32_e32 v115, 0xffff0000, v198
	v_lshlrev_b32_e32 v116, 16, v199
	v_and_b32_e32 v117, 0xffff0000, v199
	s_waitcnt lgkmcnt(0)
	v_pk_mul_f32 v[112:113], v[112:113], v[210:211] op_sel_hi:[1,0]
	v_pk_mul_f32 v[110:111], v[110:111], v[210:211] op_sel_hi:[1,0]
	s_lshl_b64 s[2:3], s[2:3], 12
	v_lshlrev_b32_e32 v118, 16, v200
	v_and_b32_e32 v119, 0xffff0000, v200
	v_lshlrev_b32_e32 v120, 16, v201
	v_and_b32_e32 v121, 0xffff0000, v201
	v_pk_fma_f32 v[112:113], v[196:197], v[112:113], v[116:117]
	v_pk_fma_f32 v[110:111], v[194:195], v[110:111], v[114:115]
	v_pk_mul_f32 v[108:109], v[108:109], v[210:211] op_sel_hi:[1,0]
	v_pk_mul_f32 v[106:107], v[106:107], v[210:211] op_sel_hi:[1,0]
	s_add_u32 s2, s58, s2
	v_pk_fma_f32 v[108:109], v[192:193], v[108:109], v[120:121]
	v_pk_fma_f32 v[106:107], v[190:191], v[106:107], v[118:119]
	ds_write_b128 v122, v[110:113] offset:16384
	ds_write_b128 v122, v[106:109] offset:16400
	s_addc_u32 s3, s59, s3
	s_waitcnt lgkmcnt(0)
	s_add_u32 s2, s2, s6
	ds_read_b128 v[108:111], v123 offset:16384
	ds_read_b128 v[112:115], v124 offset:16384
	s_addc_u32 s3, s3, s7
	s_add_u32 s2, s2, s5
	s_addc_u32 s3, s3, 0
	v_lshlrev_b32_e32 v0, 2, v213
	s_waitcnt lgkmcnt(0)
	v_lshl_add_u64 v[116:117], s[2:3], 0, v[0:1]
	v_lshlrev_b32_e32 v106, 2, v125
	v_mov_b32_e32 v107, v1
	v_lshl_add_u64 v[118:119], v[116:117], 0, v[106:107]
	s_waitcnt lgkmcnt(1)
	global_store_dwordx4 v[118:119], v[108:111], off sc1 nt
	s_nop 1
	v_lshlrev_b32_e32 v108, 2, v126
	v_mov_b32_e32 v109, v1
	v_lshl_add_u64 v[110:111], v[116:117], 0, v[108:109]
	s_waitcnt lgkmcnt(0)
	global_store_dwordx4 v[110:111], v[112:115], off sc1 nt
	s_nop 1
	v_lshlrev_b32_e32 v110, 16, v186
	v_and_b32_e32 v111, 0xffff0000, v186
	v_lshlrev_b32_e32 v112, 16, v187
	v_and_b32_e32 v113, 0xffff0000, v187
	v_pk_mul_f32 v[104:105], v[104:105], v[210:211] op_sel_hi:[1,0]
	v_pk_mul_f32 v[102:103], v[102:103], v[210:211] op_sel_hi:[1,0]
	v_lshlrev_b32_e32 v114, 16, v188
	v_and_b32_e32 v115, 0xffff0000, v188
	v_lshlrev_b32_e32 v118, 16, v189
	v_and_b32_e32 v119, 0xffff0000, v189
	v_pk_fma_f32 v[104:105], v[184:185], v[104:105], v[112:113]
	v_pk_fma_f32 v[102:103], v[182:183], v[102:103], v[110:111]
	v_pk_mul_f32 v[100:101], v[100:101], v[210:211] op_sel_hi:[1,0]
	v_pk_mul_f32 v[98:99], v[98:99], v[210:211] op_sel_hi:[1,0]
	v_pk_fma_f32 v[100:101], v[180:181], v[100:101], v[118:119]
	v_pk_fma_f32 v[98:99], v[178:179], v[98:99], v[114:115]
	ds_write_b128 v122, v[102:105] offset:16384
	ds_write_b128 v122, v[98:101] offset:16400
	s_waitcnt lgkmcnt(0)
	ds_read_b128 v[98:101], v123 offset:16384
	ds_read_b128 v[102:105], v124 offset:16384
	s_waitcnt lgkmcnt(0)
	v_lshl_add_u64 v[110:111], v[116:117], 0, s[8:9]
	v_lshl_add_u64 v[112:113], v[110:111], 0, v[106:107]
	s_waitcnt lgkmcnt(1)
	global_store_dwordx4 v[112:113], v[98:101], off sc1 nt
	s_nop 1
	v_lshl_add_u64 v[98:99], v[110:111], 0, v[108:109]
	s_waitcnt lgkmcnt(0)
	global_store_dwordx4 v[98:99], v[102:105], off sc1 nt
	s_nop 1
	v_mov_b32_e32 v98, 0x7fc00000
	s_and_b64 vcc, exec, s[0:1]
	v_mov_b32_e32 v100, 0x7fc00000
	s_cbranch_vccnz .LBB0_926
	ds_read_b32 v100, v211 offset:8320
.LBB0_926:
	s_or_b32 s2, s4, 32
	s_ashr_i32 s3, s2, 31
	v_lshlrev_b32_e32 v102, 16, v174
	v_and_b32_e32 v103, 0xffff0000, v174
	v_lshlrev_b32_e32 v104, 16, v175
	v_and_b32_e32 v105, 0xffff0000, v175
	s_waitcnt lgkmcnt(0)
	v_pk_mul_f32 v[96:97], v[96:97], v[100:101] op_sel_hi:[1,0]
	v_pk_mul_f32 v[94:95], v[94:95], v[100:101] op_sel_hi:[1,0]
	s_lshl_b64 s[2:3], s[2:3], 12
	v_lshlrev_b32_e32 v110, 16, v176
	v_and_b32_e32 v111, 0xffff0000, v176
	v_lshlrev_b32_e32 v112, 16, v177
	v_and_b32_e32 v113, 0xffff0000, v177
	v_pk_fma_f32 v[96:97], v[196:197], v[96:97], v[104:105]
	v_pk_fma_f32 v[94:95], v[194:195], v[94:95], v[102:103]
	v_pk_mul_f32 v[92:93], v[92:93], v[100:101] op_sel_hi:[1,0]
	v_pk_mul_f32 v[90:91], v[90:91], v[100:101] op_sel_hi:[1,0]
	s_add_u32 s2, s58, s2
	v_pk_fma_f32 v[92:93], v[192:193], v[92:93], v[112:113]
	v_pk_fma_f32 v[90:91], v[190:191], v[90:91], v[110:111]
	ds_write_b128 v122, v[94:97] offset:16384
	ds_write_b128 v122, v[90:93] offset:16400
	s_addc_u32 s3, s59, s3
	s_waitcnt lgkmcnt(0)
	s_add_u32 s2, s2, s6
	ds_read_b128 v[90:93], v123 offset:16384
	ds_read_b128 v[94:97], v124 offset:16384
	s_addc_u32 s3, s3, s7
	s_add_u32 s2, s2, s5
	s_addc_u32 s3, s3, 0
	v_mov_b32_e32 v1, 0
	s_waitcnt lgkmcnt(0)
	v_lshl_add_u64 v[102:103], s[2:3], 0, v[0:1]
	v_mov_b32_e32 v107, v1
	v_mov_b32_e32 v109, v1
	v_lshl_add_u64 v[104:105], v[102:103], 0, v[106:107]
	s_waitcnt lgkmcnt(1)
	global_store_dwordx4 v[104:105], v[90:93], off sc1 nt
	s_nop 1
	v_lshl_add_u64 v[90:91], v[102:103], 0, v[108:109]
	s_waitcnt lgkmcnt(0)
	global_store_dwordx4 v[90:91], v[94:97], off sc1 nt
	s_nop 1
	v_lshlrev_b32_e32 v90, 16, v170
	v_and_b32_e32 v91, 0xffff0000, v170
	v_lshlrev_b32_e32 v92, 16, v171
	v_and_b32_e32 v93, 0xffff0000, v171
	v_pk_mul_f32 v[88:89], v[88:89], v[100:101] op_sel_hi:[1,0]
	v_pk_mul_f32 v[86:87], v[86:87], v[100:101] op_sel_hi:[1,0]
	v_lshlrev_b32_e32 v94, 16, v172
	v_and_b32_e32 v95, 0xffff0000, v172
	v_lshlrev_b32_e32 v96, 16, v173
	v_and_b32_e32 v97, 0xffff0000, v173
	v_pk_fma_f32 v[88:89], v[184:185], v[88:89], v[92:93]
	v_pk_fma_f32 v[86:87], v[182:183], v[86:87], v[90:91]
	v_pk_mul_f32 v[84:85], v[84:85], v[100:101] op_sel_hi:[1,0]
	v_pk_mul_f32 v[82:83], v[82:83], v[100:101] op_sel_hi:[1,0]
	v_pk_fma_f32 v[84:85], v[180:181], v[84:85], v[96:97]
	v_pk_fma_f32 v[82:83], v[178:179], v[82:83], v[94:95]
	ds_write_b128 v122, v[86:89] offset:16384
	ds_write_b128 v122, v[82:85] offset:16400
	s_waitcnt lgkmcnt(0)
	ds_read_b128 v[82:85], v123 offset:16384
	ds_read_b128 v[86:89], v124 offset:16384
	s_mov_b64 s[2:3], 0x200
	s_waitcnt lgkmcnt(0)
	v_lshl_add_u64 v[90:91], v[102:103], 0, s[2:3]
	v_lshl_add_u64 v[92:93], v[90:91], 0, v[106:107]
	s_waitcnt lgkmcnt(1)
	global_store_dwordx4 v[92:93], v[82:85], off sc1 nt
	s_nop 1
	v_lshl_add_u64 v[82:83], v[90:91], 0, v[108:109]
	s_waitcnt lgkmcnt(0)
	global_store_dwordx4 v[82:83], v[86:89], off sc1 nt
	s_nop 1
	s_and_b64 vcc, exec, s[0:1]
	s_cbranch_vccnz .LBB0_928
	ds_read_b32 v98, v211 offset:8384
.LBB0_928:
	s_or_b32 s8, s4, 48
	s_ashr_i32 s9, s8, 31
	v_lshlrev_b32_e32 v82, 16, v166
	v_and_b32_e32 v83, 0xffff0000, v166
	v_lshlrev_b32_e32 v84, 16, v167
	v_and_b32_e32 v85, 0xffff0000, v167
	s_waitcnt lgkmcnt(0)
	v_pk_mul_f32 v[80:81], v[80:81], v[98:99] op_sel_hi:[1,0]
	v_pk_mul_f32 v[78:79], v[78:79], v[98:99] op_sel_hi:[1,0]
	s_lshl_b64 s[8:9], s[8:9], 12
	v_lshlrev_b32_e32 v86, 16, v168
	v_and_b32_e32 v87, 0xffff0000, v168
	v_lshlrev_b32_e32 v88, 16, v169
	v_and_b32_e32 v89, 0xffff0000, v169
	v_pk_fma_f32 v[80:81], v[196:197], v[80:81], v[84:85]
	v_pk_fma_f32 v[78:79], v[194:195], v[78:79], v[82:83]
	v_pk_mul_f32 v[76:77], v[76:77], v[98:99] op_sel_hi:[1,0]
	v_pk_mul_f32 v[74:75], v[74:75], v[98:99] op_sel_hi:[1,0]
	s_add_u32 s8, s58, s8
	v_pk_fma_f32 v[76:77], v[192:193], v[76:77], v[88:89]
	v_pk_fma_f32 v[74:75], v[190:191], v[74:75], v[86:87]
	ds_write_b128 v122, v[78:81] offset:16384
	ds_write_b128 v122, v[74:77] offset:16400
	s_addc_u32 s9, s59, s9
	s_waitcnt lgkmcnt(0)
	s_add_u32 s8, s8, s6
	ds_read_b128 v[74:77], v123 offset:16384
	ds_read_b128 v[78:81], v124 offset:16384
	s_addc_u32 s9, s9, s7
	s_add_u32 s8, s8, s5
	s_addc_u32 s9, s9, 0
	s_waitcnt lgkmcnt(0)
	v_lshl_add_u64 v[82:83], s[8:9], 0, v[0:1]
	v_lshl_add_u64 v[84:85], v[82:83], 0, v[106:107]
	s_waitcnt lgkmcnt(1)
	global_store_dwordx4 v[84:85], v[74:77], off sc1 nt
	s_nop 1
	v_lshl_add_u64 v[74:75], v[82:83], 0, v[108:109]
	s_waitcnt lgkmcnt(0)
	global_store_dwordx4 v[74:75], v[78:81], off sc1 nt
	s_nop 1
	v_lshlrev_b32_e32 v74, 16, v162
	v_and_b32_e32 v75, 0xffff0000, v162
	v_lshlrev_b32_e32 v76, 16, v163
	v_and_b32_e32 v77, 0xffff0000, v163
	v_pk_mul_f32 v[72:73], v[72:73], v[98:99] op_sel_hi:[1,0]
	v_pk_mul_f32 v[70:71], v[70:71], v[98:99] op_sel_hi:[1,0]
	v_lshlrev_b32_e32 v78, 16, v164
	v_and_b32_e32 v79, 0xffff0000, v164
	v_lshlrev_b32_e32 v80, 16, v165
	v_and_b32_e32 v81, 0xffff0000, v165
	v_pk_fma_f32 v[72:73], v[184:185], v[72:73], v[76:77]
	v_pk_fma_f32 v[70:71], v[182:183], v[70:71], v[74:75]
	v_pk_mul_f32 v[68:69], v[68:69], v[98:99] op_sel_hi:[1,0]
	v_pk_mul_f32 v[66:67], v[66:67], v[98:99] op_sel_hi:[1,0]
	v_pk_fma_f32 v[68:69], v[180:181], v[68:69], v[80:81]
	v_pk_fma_f32 v[66:67], v[178:179], v[66:67], v[78:79]
	ds_write_b128 v122, v[70:73] offset:16384
	ds_write_b128 v122, v[66:69] offset:16400
	s_waitcnt lgkmcnt(0)
	ds_read_b128 v[66:69], v123 offset:16384
	ds_read_b128 v[70:73], v124 offset:16384
	s_waitcnt lgkmcnt(0)
	v_lshl_add_u64 v[74:75], v[82:83], 0, s[2:3]
	v_lshl_add_u64 v[76:77], v[74:75], 0, v[106:107]
	s_waitcnt lgkmcnt(1)
	global_store_dwordx4 v[76:77], v[66:69], off sc1 nt
	s_nop 1
	v_lshl_add_u64 v[66:67], v[74:75], 0, v[108:109]
	s_waitcnt lgkmcnt(0)
	global_store_dwordx4 v[66:67], v[70:73], off sc1 nt
	s_nop 1
	v_mov_b32_e32 v66, 0x7fc00000
	s_and_b64 vcc, exec, s[0:1]
	v_mov_b32_e32 v68, 0x7fc00000
	s_cbranch_vccnz .LBB0_930
	ds_read_b32 v68, v211 offset:8704
.LBB0_930:
	s_add_i32 s2, s4, 0x80
	s_ashr_i32 s3, s2, 31
	v_lshlrev_b32_e32 v70, 16, v158
	v_and_b32_e32 v71, 0xffff0000, v158
	v_lshlrev_b32_e32 v72, 16, v159
	v_and_b32_e32 v73, 0xffff0000, v159
	s_waitcnt lgkmcnt(0)
	v_pk_mul_f32 v[64:65], v[64:65], v[68:69] op_sel_hi:[1,0]
	v_pk_mul_f32 v[62:63], v[62:63], v[68:69] op_sel_hi:[1,0]
	s_lshl_b64 s[2:3], s[2:3], 12
	v_lshlrev_b32_e32 v74, 16, v160
	v_and_b32_e32 v75, 0xffff0000, v160
	v_lshlrev_b32_e32 v76, 16, v161
	v_and_b32_e32 v77, 0xffff0000, v161
	v_pk_fma_f32 v[64:65], v[196:197], v[64:65], v[72:73]
	v_pk_fma_f32 v[62:63], v[194:195], v[62:63], v[70:71]
	v_pk_mul_f32 v[60:61], v[60:61], v[68:69] op_sel_hi:[1,0]
	v_pk_mul_f32 v[58:59], v[58:59], v[68:69] op_sel_hi:[1,0]
	s_add_u32 s2, s58, s2
	v_pk_fma_f32 v[60:61], v[192:193], v[60:61], v[76:77]
	v_pk_fma_f32 v[58:59], v[190:191], v[58:59], v[74:75]
	ds_write_b128 v122, v[62:65] offset:16384
	ds_write_b128 v122, v[58:61] offset:16400
	s_addc_u32 s3, s59, s3
	s_waitcnt lgkmcnt(0)
	s_add_u32 s2, s2, s6
	ds_read_b128 v[58:61], v123 offset:16384
	ds_read_b128 v[62:65], v124 offset:16384
	s_addc_u32 s3, s3, s7
	s_add_u32 s2, s2, s5
	s_addc_u32 s3, s3, 0
	v_mov_b32_e32 v1, 0
	s_waitcnt lgkmcnt(0)
	v_lshl_add_u64 v[70:71], s[2:3], 0, v[0:1]
	v_mov_b32_e32 v107, v1
	v_mov_b32_e32 v109, v1
	v_lshl_add_u64 v[72:73], v[70:71], 0, v[106:107]
	s_waitcnt lgkmcnt(1)
	global_store_dwordx4 v[72:73], v[58:61], off sc1 nt
	s_nop 1
	v_lshl_add_u64 v[58:59], v[70:71], 0, v[108:109]
	s_waitcnt lgkmcnt(0)
	global_store_dwordx4 v[58:59], v[62:65], off sc1 nt
	s_nop 1
	v_lshlrev_b32_e32 v58, 16, v154
	v_and_b32_e32 v59, 0xffff0000, v154
	v_lshlrev_b32_e32 v60, 16, v155
	v_and_b32_e32 v61, 0xffff0000, v155
	v_pk_mul_f32 v[56:57], v[56:57], v[68:69] op_sel_hi:[1,0]
	v_pk_mul_f32 v[54:55], v[54:55], v[68:69] op_sel_hi:[1,0]
	v_lshlrev_b32_e32 v62, 16, v156
	v_and_b32_e32 v63, 0xffff0000, v156
	v_lshlrev_b32_e32 v64, 16, v157
	v_and_b32_e32 v65, 0xffff0000, v157
	v_pk_fma_f32 v[56:57], v[184:185], v[56:57], v[60:61]
	v_pk_fma_f32 v[54:55], v[182:183], v[54:55], v[58:59]
	v_pk_mul_f32 v[52:53], v[52:53], v[68:69] op_sel_hi:[1,0]
	v_pk_mul_f32 v[50:51], v[50:51], v[68:69] op_sel_hi:[1,0]
	v_pk_fma_f32 v[52:53], v[180:181], v[52:53], v[64:65]
	v_pk_fma_f32 v[50:51], v[178:179], v[50:51], v[62:63]
	ds_write_b128 v122, v[54:57] offset:16384
	ds_write_b128 v122, v[50:53] offset:16400
	s_waitcnt lgkmcnt(0)
	ds_read_b128 v[50:53], v123 offset:16384
	ds_read_b128 v[54:57], v124 offset:16384
	s_mov_b64 s[2:3], 0x200
	s_waitcnt lgkmcnt(0)
	v_lshl_add_u64 v[58:59], v[70:71], 0, s[2:3]
	v_lshl_add_u64 v[60:61], v[58:59], 0, v[106:107]
	s_waitcnt lgkmcnt(1)
	global_store_dwordx4 v[60:61], v[50:53], off sc1 nt
	s_nop 1
	v_lshl_add_u64 v[50:51], v[58:59], 0, v[108:109]
	s_waitcnt lgkmcnt(0)
	global_store_dwordx4 v[50:51], v[54:57], off sc1 nt
	s_nop 1
	s_and_b64 vcc, exec, s[0:1]
	s_cbranch_vccnz .LBB0_932
	ds_read_b32 v66, v211 offset:8768
.LBB0_932:
	s_add_i32 s8, s4, 0x90
	s_ashr_i32 s9, s8, 31
	v_lshlrev_b32_e32 v50, 16, v150
	v_and_b32_e32 v51, 0xffff0000, v150
	v_lshlrev_b32_e32 v52, 16, v151
	v_and_b32_e32 v53, 0xffff0000, v151
	s_waitcnt lgkmcnt(0)
	v_pk_mul_f32 v[48:49], v[48:49], v[66:67] op_sel_hi:[1,0]
	v_pk_mul_f32 v[46:47], v[46:47], v[66:67] op_sel_hi:[1,0]
	s_lshl_b64 s[8:9], s[8:9], 12
	v_lshlrev_b32_e32 v54, 16, v152
	v_and_b32_e32 v55, 0xffff0000, v152
	v_lshlrev_b32_e32 v56, 16, v153
	v_and_b32_e32 v57, 0xffff0000, v153
	v_pk_fma_f32 v[48:49], v[196:197], v[48:49], v[52:53]
	v_pk_fma_f32 v[46:47], v[194:195], v[46:47], v[50:51]
	v_pk_mul_f32 v[44:45], v[44:45], v[66:67] op_sel_hi:[1,0]
	v_pk_mul_f32 v[42:43], v[42:43], v[66:67] op_sel_hi:[1,0]
	s_add_u32 s8, s58, s8
	v_pk_fma_f32 v[44:45], v[192:193], v[44:45], v[56:57]
	v_pk_fma_f32 v[42:43], v[190:191], v[42:43], v[54:55]
	ds_write_b128 v122, v[46:49] offset:16384
	ds_write_b128 v122, v[42:45] offset:16400
	s_addc_u32 s9, s59, s9
	s_waitcnt lgkmcnt(0)
	s_add_u32 s8, s8, s6
	ds_read_b128 v[42:45], v123 offset:16384
	ds_read_b128 v[46:49], v124 offset:16384
	s_addc_u32 s9, s9, s7
	s_add_u32 s8, s8, s5
	s_addc_u32 s9, s9, 0
	s_waitcnt lgkmcnt(0)
	v_lshl_add_u64 v[50:51], s[8:9], 0, v[0:1]
	v_lshl_add_u64 v[52:53], v[50:51], 0, v[106:107]
	s_waitcnt lgkmcnt(1)
	global_store_dwordx4 v[52:53], v[42:45], off sc1 nt
	s_nop 1
	v_lshl_add_u64 v[42:43], v[50:51], 0, v[108:109]
	s_waitcnt lgkmcnt(0)
	global_store_dwordx4 v[42:43], v[46:49], off sc1 nt
	s_nop 1
	v_lshlrev_b32_e32 v42, 16, v146
	v_and_b32_e32 v43, 0xffff0000, v146
	v_lshlrev_b32_e32 v44, 16, v147
	v_and_b32_e32 v45, 0xffff0000, v147
	v_pk_mul_f32 v[40:41], v[40:41], v[66:67] op_sel_hi:[1,0]
	v_pk_mul_f32 v[38:39], v[38:39], v[66:67] op_sel_hi:[1,0]
	v_lshlrev_b32_e32 v46, 16, v148
	v_and_b32_e32 v47, 0xffff0000, v148
	v_lshlrev_b32_e32 v48, 16, v149
	v_and_b32_e32 v49, 0xffff0000, v149
	v_pk_fma_f32 v[40:41], v[184:185], v[40:41], v[44:45]
	v_pk_fma_f32 v[38:39], v[182:183], v[38:39], v[42:43]
	v_pk_mul_f32 v[36:37], v[36:37], v[66:67] op_sel_hi:[1,0]
	v_pk_mul_f32 v[34:35], v[34:35], v[66:67] op_sel_hi:[1,0]
	v_pk_fma_f32 v[36:37], v[180:181], v[36:37], v[48:49]
	v_pk_fma_f32 v[34:35], v[178:179], v[34:35], v[46:47]
	ds_write_b128 v122, v[38:41] offset:16384
	ds_write_b128 v122, v[34:37] offset:16400
	s_waitcnt lgkmcnt(0)
	ds_read_b128 v[34:37], v123 offset:16384
	ds_read_b128 v[38:41], v124 offset:16384
	s_waitcnt lgkmcnt(0)
	v_lshl_add_u64 v[42:43], v[50:51], 0, s[2:3]
	v_lshl_add_u64 v[44:45], v[42:43], 0, v[106:107]
	s_waitcnt lgkmcnt(1)
	global_store_dwordx4 v[44:45], v[34:37], off sc1 nt
	s_nop 1
	v_lshl_add_u64 v[34:35], v[42:43], 0, v[108:109]
	s_waitcnt lgkmcnt(0)
	global_store_dwordx4 v[34:35], v[38:41], off sc1 nt
	s_nop 1
	v_mov_b32_e32 v34, 0x7fc00000
	s_and_b64 vcc, exec, s[0:1]
	v_mov_b32_e32 v36, 0x7fc00000
	s_cbranch_vccnz .LBB0_934
	ds_read_b32 v36, v211 offset:8832
.LBB0_934:
	s_add_i32 s2, s4, 0xa0
	s_ashr_i32 s3, s2, 31
	v_lshlrev_b32_e32 v38, 16, v142
	v_and_b32_e32 v39, 0xffff0000, v142
	v_lshlrev_b32_e32 v40, 16, v143
	v_and_b32_e32 v41, 0xffff0000, v143
	s_waitcnt lgkmcnt(0)
	v_pk_mul_f32 v[32:33], v[32:33], v[36:37] op_sel_hi:[1,0]
	v_pk_mul_f32 v[30:31], v[30:31], v[36:37] op_sel_hi:[1,0]
	s_lshl_b64 s[2:3], s[2:3], 12
	v_lshlrev_b32_e32 v42, 16, v144
	v_and_b32_e32 v43, 0xffff0000, v144
	v_lshlrev_b32_e32 v44, 16, v145
	v_and_b32_e32 v45, 0xffff0000, v145
	v_pk_fma_f32 v[32:33], v[196:197], v[32:33], v[40:41]
	v_pk_fma_f32 v[30:31], v[194:195], v[30:31], v[38:39]
	v_pk_mul_f32 v[28:29], v[28:29], v[36:37] op_sel_hi:[1,0]
	v_pk_mul_f32 v[26:27], v[26:27], v[36:37] op_sel_hi:[1,0]
	s_add_u32 s2, s58, s2
	v_pk_fma_f32 v[28:29], v[192:193], v[28:29], v[44:45]
	v_pk_fma_f32 v[26:27], v[190:191], v[26:27], v[42:43]
	ds_write_b128 v122, v[30:33] offset:16384
	ds_write_b128 v122, v[26:29] offset:16400
	s_addc_u32 s3, s59, s3
	s_waitcnt lgkmcnt(0)
	s_add_u32 s2, s2, s6
	ds_read_b128 v[26:29], v123 offset:16384
	ds_read_b128 v[30:33], v124 offset:16384
	s_addc_u32 s3, s3, s7
	s_add_u32 s2, s2, s5
	s_addc_u32 s3, s3, 0
	v_mov_b32_e32 v1, 0
	s_waitcnt lgkmcnt(0)
	v_lshl_add_u64 v[38:39], s[2:3], 0, v[0:1]
	v_mov_b32_e32 v107, v1
	v_mov_b32_e32 v109, v1
	v_lshl_add_u64 v[40:41], v[38:39], 0, v[106:107]
	s_waitcnt lgkmcnt(1)
	global_store_dwordx4 v[40:41], v[26:29], off sc1 nt
	s_nop 1
	v_lshl_add_u64 v[26:27], v[38:39], 0, v[108:109]
	s_waitcnt lgkmcnt(0)
	global_store_dwordx4 v[26:27], v[30:33], off sc1 nt
	s_nop 1
	v_lshlrev_b32_e32 v26, 16, v138
	v_and_b32_e32 v27, 0xffff0000, v138
	v_lshlrev_b32_e32 v28, 16, v139
	v_and_b32_e32 v29, 0xffff0000, v139
	v_pk_mul_f32 v[24:25], v[24:25], v[36:37] op_sel_hi:[1,0]
	v_pk_mul_f32 v[22:23], v[22:23], v[36:37] op_sel_hi:[1,0]
	v_lshlrev_b32_e32 v30, 16, v140
	v_and_b32_e32 v31, 0xffff0000, v140
	v_lshlrev_b32_e32 v32, 16, v141
	v_and_b32_e32 v33, 0xffff0000, v141
	v_pk_fma_f32 v[24:25], v[184:185], v[24:25], v[28:29]
	v_pk_fma_f32 v[22:23], v[182:183], v[22:23], v[26:27]
	v_pk_mul_f32 v[20:21], v[20:21], v[36:37] op_sel_hi:[1,0]
	v_pk_mul_f32 v[18:19], v[18:19], v[36:37] op_sel_hi:[1,0]
	v_pk_fma_f32 v[20:21], v[180:181], v[20:21], v[32:33]
	v_pk_fma_f32 v[18:19], v[178:179], v[18:19], v[30:31]
	ds_write_b128 v122, v[22:25] offset:16384
	ds_write_b128 v122, v[18:21] offset:16400
	s_waitcnt lgkmcnt(0)
	ds_read_b128 v[18:21], v123 offset:16384
	ds_read_b128 v[22:25], v124 offset:16384
	s_mov_b64 s[2:3], 0x200
	s_waitcnt lgkmcnt(0)
	v_lshl_add_u64 v[26:27], v[38:39], 0, s[2:3]
	v_lshl_add_u64 v[28:29], v[26:27], 0, v[106:107]
	s_waitcnt lgkmcnt(1)
	global_store_dwordx4 v[28:29], v[18:21], off sc1 nt
	s_nop 1
	v_lshl_add_u64 v[18:19], v[26:27], 0, v[108:109]
	s_waitcnt lgkmcnt(0)
	global_store_dwordx4 v[18:19], v[22:25], off sc1 nt
	s_nop 1
	s_and_b64 vcc, exec, s[0:1]
	s_cbranch_vccnz .LBB0_936
	ds_read_b32 v34, v211 offset:8896
.LBB0_936:
	s_add_i32 s0, s4, 0xb0
	s_ashr_i32 s1, s0, 31
	s_lshl_b64 s[0:1], s[0:1], 12
	v_lshlrev_b32_e32 v18, 16, v134
	v_and_b32_e32 v19, 0xffff0000, v134
	v_lshlrev_b32_e32 v20, 16, v135
	v_and_b32_e32 v21, 0xffff0000, v135
	s_waitcnt lgkmcnt(0)
	v_pk_mul_f32 v[16:17], v[16:17], v[34:35] op_sel_hi:[1,0]
	v_pk_mul_f32 v[14:15], v[14:15], v[34:35] op_sel_hi:[1,0]
	s_add_u32 s0, s58, s0
	v_lshlrev_b32_e32 v22, 16, v136
	v_and_b32_e32 v23, 0xffff0000, v136
	v_lshlrev_b32_e32 v24, 16, v137
	v_and_b32_e32 v25, 0xffff0000, v137
	v_pk_fma_f32 v[16:17], v[196:197], v[16:17], v[20:21]
	v_pk_fma_f32 v[14:15], v[194:195], v[14:15], v[18:19]
	v_pk_mul_f32 v[12:13], v[12:13], v[34:35] op_sel_hi:[1,0]
	v_pk_mul_f32 v[10:11], v[10:11], v[34:35] op_sel_hi:[1,0]
	s_addc_u32 s1, s59, s1
	v_pk_fma_f32 v[12:13], v[192:193], v[12:13], v[24:25]
	v_pk_fma_f32 v[10:11], v[190:191], v[10:11], v[22:23]
	ds_write_b128 v122, v[14:17] offset:16384
	ds_write_b128 v122, v[10:13] offset:16400
	s_add_u32 s0, s0, s6
	s_waitcnt lgkmcnt(0)
	s_addc_u32 s1, s1, s7
	ds_read_b128 v[10:13], v123 offset:16384
	ds_read_b128 v[14:17], v124 offset:16384
	s_add_u32 s0, s0, s5
	s_addc_u32 s1, s1, 0
	v_lshl_add_u64 v[18:19], s[0:1], 0, v[0:1]
	s_waitcnt lgkmcnt(0)
	v_lshl_add_u64 v[0:1], v[18:19], 0, v[106:107]
	s_waitcnt lgkmcnt(1)
	global_store_dwordx4 v[0:1], v[10:13], off sc1 nt
	s_nop 1
	v_lshl_add_u64 v[0:1], v[18:19], 0, v[108:109]
	s_waitcnt lgkmcnt(0)
	global_store_dwordx4 v[0:1], v[14:17], off sc1 nt
	s_nop 1
	v_lshlrev_b32_e32 v0, 16, v130
	v_and_b32_e32 v1, 0xffff0000, v130
	v_lshlrev_b32_e32 v10, 16, v131
	v_and_b32_e32 v11, 0xffff0000, v131
	v_pk_mul_f32 v[8:9], v[8:9], v[34:35] op_sel_hi:[1,0]
	v_pk_mul_f32 v[6:7], v[6:7], v[34:35] op_sel_hi:[1,0]
	v_lshlrev_b32_e32 v12, 16, v132
	v_and_b32_e32 v13, 0xffff0000, v132
	v_lshlrev_b32_e32 v14, 16, v133
	v_and_b32_e32 v15, 0xffff0000, v133
	v_pk_fma_f32 v[8:9], v[184:185], v[8:9], v[10:11]
	v_pk_fma_f32 v[6:7], v[182:183], v[6:7], v[0:1]
	v_pk_mul_f32 v[0:1], v[4:5], v[34:35] op_sel_hi:[1,0]
	v_pk_mul_f32 v[4:5], v[2:3], v[34:35] op_sel_hi:[1,0]
	v_pk_fma_f32 v[2:3], v[180:181], v[0:1], v[14:15]
	v_pk_fma_f32 v[0:1], v[178:179], v[4:5], v[12:13]
	ds_write_b128 v122, v[6:9] offset:16384
	ds_write_b128 v122, v[0:3] offset:16400
	s_waitcnt lgkmcnt(0)
	ds_read_b128 v[0:3], v123 offset:16384
	ds_read_b128 v[4:7], v124 offset:16384
	s_waitcnt lgkmcnt(0)
	v_lshl_add_u64 v[8:9], v[18:19], 0, s[2:3]
	v_lshl_add_u64 v[10:11], v[8:9], 0, v[106:107]
	s_waitcnt lgkmcnt(1)
	global_store_dwordx4 v[10:11], v[0:3], off sc1 nt
	s_nop 1
	v_lshl_add_u64 v[0:1], v[8:9], 0, v[108:109]
	s_waitcnt lgkmcnt(0)
	global_store_dwordx4 v[0:1], v[4:7], off sc1 nt
	s_nop 1
